# speedup vs baseline: 1.0040x; 1.0032x over previous
; DI unsigned pk_bf16(float lo, float hi) { f32x2_t v = {lo, hi}; return __builtin_bit_cast(unsigned, __builtin_convertvector(v, bf16x2_t)); }
; DI float bflo(unsigned u) { return __uint_as_float(u << 16); }
; DI float bfhi(unsigned u) { return __uint_as_float(u & 0xffff0000u); }
; DI float fgelu(float x) { return x * fsigmoid(1.5957691216057308f * (x + 0.044715f * x * x * x)); }
; DI void conv8(const u32x4& v0, const u32x4& v1, const u32x4& v2, const u32x4& g0, const u32x4& g1, const u32x4& g2,
;               const float (&wv)[3][8], const float (&wg)[3][8], const float (&bv)[8], const float (&bg)[8], u32x4& o) {
; #pragma unroll
;   for (int e = 0; e < 4; ++e) {
;     const float cv0 = bv[2 * e] + wv[0][2 * e] * bflo(v2[e]) + wv[1][2 * e] * bflo(v1[e]) + wv[2][2 * e] * bflo(v0[e]);
;     const float cv1 = bv[2 * e + 1] + wv[0][2 * e + 1] * bfhi(v2[e]) + wv[1][2 * e + 1] * bfhi(v1[e]) + wv[2][2 * e + 1] * bfhi(v0[e]);
;     const float cg0 = bg[2 * e] + wg[0][2 * e] * bflo(g2[e]) + wg[1][2 * e] * bflo(g1[e]) + wg[2][2 * e] * bflo(g0[e]);
;     const float cg1 = bg[2 * e + 1] + wg[0][2 * e + 1] * bfhi(g2[e]) + wg[1][2 * e + 1] * bfhi(g1[e]) + wg[2][2 * e + 1] * bfhi(g0[e]);
;     o[e] = pk_bf16(fgelu(cg0) * cv0, fgelu(cg1) * cv1);
;   }
; DI void p8_phase(const Params& p, int layer, char* lds) {
;     ...
; #pragma unroll 2
;         for (int i = 0; i < 8; ++i) {
;           const int t = (tid >> 4) + 32 * i;
;           const u32x4 v0 = TLD(t, 0), g0 = TLD(t, 1);
;           if (t >= 2) {
;             const u32x4 v1 = TLD(t - 1, 0), g1 = TLD(t - 1, 1), v2 = TLD(t - 2, 0), g2 = TLD(t - 2, 1);
;             u32x4 o; conv8(v0, v1, v2, g0, g1, g2, wv, wg, bv, bg, o);
;             *(u32x4*)(hb + (size_t)t * DFF) = o;
.LBB0_1177:
	v_add_u32_e32 v100, s7, v99
	v_add_u32_e32 v101, s7, v98
	s_waitcnt lgkmcnt(1)
	ds_read_b128 v[70:73], v100
	s_waitcnt lgkmcnt(1)
	ds_read_b128 v[66:69], v101
	v_cmp_lt_i32_e32 vcc, 1, v64
	s_and_saveexec_b64 s[8:9], vcc
	s_cbranch_execz .LBB0_1179
	v_add_u32_e32 v74, 0xffffffbe, v96
	v_add_u32_e32 v78, 0xffffffbc, v96
	v_bitop3_b32 v75, v74, v94, 14 bitop3:0x6c
	v_bitop3_b32 v79, v78, v94, 14 bitop3:0x6c
	v_lshlrev_b32_e32 v75, 3, v75
	v_lshlrev_b32_e32 v79, 3, v79
	v_add3_u32 v75, v97, v75, s7
	v_add3_u32 v79, v97, v79, s7
	v_add_u32_e32 v75, 0xfffffe00, v75
	v_bitop3_b32 v74, v74, v95, 14 bitop3:0x6c
	v_add_u32_e32 v79, 0xfffffc00, v79
	v_bitop3_b32 v78, v78, v95, 14 bitop3:0x6c
	ds_read_b128 v[82:85], v75
	ds_read_b128 v[86:89], v79
	v_lshlrev_b32_e32 v74, 3, v74
	v_lshlrev_b32_e32 v78, 3, v78
	v_add3_u32 v74, v97, v74, s7
	v_add3_u32 v78, v97, v78, s7
	v_add_u32_e32 v74, 0xfffffe00, v74
	v_add_u32_e32 v78, 0xfffffc00, v78
	ds_read_b128 v[74:77], v74
	ds_read_b128 v[78:81], v78
	s_waitcnt lgkmcnt(2)
	v_lshlrev_b32_e32 v102, 16, v86
	v_and_b32_e32 v103, 0xffff0000, v86
	v_pk_fma_f32 v[102:103], v[20:21], v[102:103], v[60:61]
	v_lshlrev_b32_e32 v104, 16, v82
	v_and_b32_e32 v105, 0xffff0000, v82
	v_lshlrev_b32_e32 v86, 16, v87
	v_and_b32_e32 v87, 0xffff0000, v87
	v_pk_fma_f32 v[102:103], v[24:25], v[104:105], v[102:103]
	v_lshlrev_b32_e32 v104, 16, v70
	v_and_b32_e32 v105, 0xffff0000, v70
	v_pk_fma_f32 v[86:87], v[22:23], v[86:87], v[62:63]
	v_lshlrev_b32_e32 v82, 16, v83
	v_and_b32_e32 v83, 0xffff0000, v83
	v_pk_fma_f32 v[102:103], v[40:41], v[104:105], v[102:103]
	s_waitcnt lgkmcnt(0)
	v_lshlrev_b32_e32 v104, 16, v78
	v_and_b32_e32 v105, 0xffff0000, v78
	v_pk_fma_f32 v[82:83], v[26:27], v[82:83], v[86:87]
	v_lshlrev_b32_e32 v86, 16, v71
	v_and_b32_e32 v87, 0xffff0000, v71
	v_lshlrev_b32_e32 v78, 16, v79
	v_and_b32_e32 v79, 0xffff0000, v79
	v_pk_fma_f32 v[82:83], v[42:43], v[86:87], v[82:83]
	v_pk_fma_f32 v[78:79], v[2:3], v[78:79], v[10:11]
	v_lshlrev_b32_e32 v86, 16, v75
	v_and_b32_e32 v87, 0xffff0000, v75
	v_pk_fma_f32 v[78:79], v[30:31], v[86:87], v[78:79]
	v_lshlrev_b32_e32 v86, 16, v67
	v_and_b32_e32 v87, 0xffff0000, v67
	v_pk_fma_f32 v[78:79], v[46:47], v[86:87], v[78:79]
	v_pk_fma_f32 v[104:105], v[0:1], v[104:105], v[8:9]
	v_mul_f32_e32 v75, 0x3d372713, v78
	v_mul_f32_e32 v75, v78, v75
	v_fma_f32 v75, v78, v75, v78
	v_mul_f32_e32 v75, 0xc0135761, v75
	v_exp_f32_e32 v75, v75
	v_lshlrev_b32_e32 v106, 16, v74
	v_and_b32_e32 v107, 0xffff0000, v74
	v_pk_fma_f32 v[104:105], v[28:29], v[106:107], v[104:105]
	v_add_f32_e32 v75, 1.0, v75
	v_rcp_f32_e32 v86, v75
	v_mul_f32_e32 v75, 0x3d372713, v79
	v_mul_f32_e32 v75, v79, v75
	v_fma_f32 v75, v79, v75, v79
	v_mul_f32_e32 v75, 0xc0135761, v75
	v_exp_f32_e32 v75, v75
	v_lshlrev_b32_e32 v106, 16, v66
	v_and_b32_e32 v107, 0xffff0000, v66
	v_pk_fma_f32 v[104:105], v[44:45], v[106:107], v[104:105]
	v_add_f32_e32 v75, 1.0, v75
	v_rcp_f32_e32 v87, v75
	v_mul_f32_e32 v74, 0x3d372713, v104
	v_mul_f32_e32 v74, v104, v74
	v_fma_f32 v74, v104, v74, v104
	v_pk_mul_f32 v[78:79], v[78:79], v[86:87]
	v_lshlrev_b32_e32 v86, 16, v76
	v_pk_mul_f32 v[78:79], v[82:83], v[78:79]
	v_lshlrev_b32_e32 v82, 16, v84
	v_cvt_pk_bf16_f32 v75, v78, v79
	v_lshlrev_b32_e32 v78, 16, v88
	v_and_b32_e32 v79, 0xffff0000, v88
	v_pk_fma_f32 v[78:79], v[16:17], v[78:79], v[56:57]
	v_and_b32_e32 v83, 0xffff0000, v84
	v_pk_fma_f32 v[78:79], v[32:33], v[82:83], v[78:79]
	v_lshlrev_b32_e32 v82, 16, v72
	v_and_b32_e32 v83, 0xffff0000, v72
	v_pk_fma_f32 v[78:79], v[48:49], v[82:83], v[78:79]
	v_lshlrev_b32_e32 v82, 16, v80
	v_and_b32_e32 v83, 0xffff0000, v80
	v_pk_fma_f32 v[82:83], v[4:5], v[82:83], v[12:13]
	v_and_b32_e32 v87, 0xffff0000, v76
	v_pk_fma_f32 v[82:83], v[36:37], v[86:87], v[82:83]
	v_lshlrev_b32_e32 v86, 16, v68
	v_and_b32_e32 v87, 0xffff0000, v68
	v_pk_fma_f32 v[82:83], v[52:53], v[86:87], v[82:83]
	v_lshlrev_b32_e32 v80, 16, v81
	v_mul_f32_e32 v76, 0x3d372713, v82
	v_mul_f32_e32 v76, v82, v76
	v_fma_f32 v76, v82, v76, v82
	v_mul_f32_e32 v76, 0xc0135761, v76
	v_exp_f32_e32 v76, v76
	v_and_b32_e32 v81, 0xffff0000, v81
	v_pk_fma_f32 v[80:81], v[6:7], v[80:81], v[14:15]
	v_mul_f32_e32 v74, 0x3fcc422a, v74
	v_add_f32_e32 v76, 1.0, v76
	v_rcp_f32_e32 v86, v76
	v_mul_f32_e32 v76, 0x3d372713, v83
	v_mul_f32_e32 v76, v83, v76
	v_fma_f32 v76, v83, v76, v83
	v_mul_f32_e32 v76, 0xc0135761, v76
	v_exp_f32_e32 v76, v76
	v_mul_f32_e32 v74, 0xbfb8aa3b, v74
	v_exp_f32_e32 v74, v74
	v_add_f32_e32 v76, 1.0, v76
	v_rcp_f32_e32 v87, v76
	v_add_f32_e32 v74, 1.0, v74
	v_rcp_f32_e32 v106, v74
	v_mul_f32_e32 v74, 0x3d372713, v105
	v_pk_mul_f32 v[82:83], v[82:83], v[86:87]
	v_mul_f32_e32 v74, v105, v74
	v_pk_mul_f32 v[78:79], v[78:79], v[82:83]
	v_lshlrev_b32_e32 v82, 16, v85
	v_cvt_pk_bf16_f32 v76, v78, v79
	v_lshlrev_b32_e32 v78, 16, v89
	v_and_b32_e32 v79, 0xffff0000, v89
	v_pk_fma_f32 v[78:79], v[18:19], v[78:79], v[58:59]
	v_and_b32_e32 v83, 0xffff0000, v85
	v_pk_fma_f32 v[78:79], v[34:35], v[82:83], v[78:79]
	v_lshlrev_b32_e32 v82, 16, v73
	v_and_b32_e32 v83, 0xffff0000, v73
	v_pk_fma_f32 v[78:79], v[50:51], v[82:83], v[78:79]
	v_lshlrev_b32_e32 v82, 16, v77
	v_and_b32_e32 v83, 0xffff0000, v77
	v_pk_fma_f32 v[80:81], v[38:39], v[82:83], v[80:81]
	v_lshlrev_b32_e32 v82, 16, v69
	v_and_b32_e32 v83, 0xffff0000, v69
	v_pk_fma_f32 v[80:81], v[54:55], v[82:83], v[80:81]
	v_fma_f32 v74, v105, v74, v105
	v_mul_f32_e32 v77, 0x3d372713, v80
	v_mul_f32_e32 v77, v80, v77
	v_fma_f32 v77, v80, v77, v80
	v_mul_f32_e32 v77, 0xc0135761, v77
	v_exp_f32_e32 v77, v77
	v_mul_f32_e32 v74, 0xc0135761, v74
	v_exp_f32_e32 v74, v74
	v_add_f32_e32 v77, 1.0, v77
	v_rcp_f32_e32 v82, v77
	v_mul_f32_e32 v77, 0x3d372713, v81
	v_mul_f32_e32 v77, v81, v77
	v_fma_f32 v77, v81, v77, v81
	v_mul_f32_e32 v77, 0xc0135761, v77
	v_exp_f32_e32 v77, v77
	v_add_f32_e32 v74, 1.0, v74
	v_rcp_f32_e32 v107, v74
	v_add_f32_e32 v77, 1.0, v77
	v_rcp_f32_e32 v83, v77
	v_pk_mul_f32 v[104:105], v[104:105], v[106:107]
	v_pk_mul_f32 v[80:81], v[80:81], v[82:83]
	v_pk_mul_f32 v[102:103], v[102:103], v[104:105]
	v_pk_mul_f32 v[78:79], v[78:79], v[80:81]
	v_cvt_pk_bf16_f32 v74, v102, v103
	v_cvt_pk_bf16_f32 v77, v78, v79
	v_mad_u64_u32 v[78:79], s[22:23], v64, s6, v[90:91]
	global_store_dwordx4 v[78:79], v[74:77], off sc0 sc1

; DI unsigned pk_bf16(float lo, float hi) { f32x2_t v = {lo, hi}; return __builtin_bit_cast(unsigned, __builtin_convertvector(v, bf16x2_t)); }
; DI float bflo(unsigned u) { return __uint_as_float(u << 16); }
; DI float bfhi(unsigned u) { return __uint_as_float(u & 0xffff0000u); }
; DI float fgelu(float x) { return x * fsigmoid(1.5957691216057308f * (x + 0.044715f * x * x * x)); }
; DI void conv8(const u32x4& v0, const u32x4& v1, const u32x4& v2, const u32x4& g0, const u32x4& g1, const u32x4& g2,
;               const float (&wv)[3][8], const float (&wg)[3][8], const float (&bv)[8], const float (&bg)[8], u32x4& o) {
; #pragma unroll
;   for (int e = 0; e < 4; ++e) {
;     const float cv0 = bv[2 * e] + wv[0][2 * e] * bflo(v2[e]) + wv[1][2 * e] * bflo(v1[e]) + wv[2][2 * e] * bflo(v0[e]);
;     const float cv1 = bv[2 * e + 1] + wv[0][2 * e + 1] * bfhi(v2[e]) + wv[1][2 * e + 1] * bfhi(v1[e]) + wv[2][2 * e + 1] * bfhi(v0[e]);
;     const float cg0 = bg[2 * e] + wg[0][2 * e] * bflo(g2[e]) + wg[1][2 * e] * bflo(g1[e]) + wg[2][2 * e] * bflo(g0[e]);
;     const float cg1 = bg[2 * e + 1] + wg[0][2 * e + 1] * bfhi(g2[e]) + wg[1][2 * e + 1] * bfhi(g1[e]) + wg[2][2 * e + 1] * bfhi(g0[e]);
;     o[e] = pk_bf16(fgelu(cg0) * cv0, fgelu(cg1) * cv1);
;   }
; DI void p8_phase(const Params& p, int layer, char* lds) {
;     ...
; #pragma unroll 2
;         for (int i = 0; i < 8; ++i) {
;           const int t = (tid >> 4) + 32 * i;
;           const u32x4 v0 = TLD(t, 0), g0 = TLD(t, 1);
;           if (t >= 2) {
;             const u32x4 v1 = TLD(t - 1, 0), g1 = TLD(t - 1, 1), v2 = TLD(t - 2, 0), g2 = TLD(t - 2, 1);
;             u32x4 o; conv8(v0, v1, v2, g0, g1, g2, wv, wg, bv, bg, o);
;             *(u32x4*)(hb + (size_t)t * DFF) = o;
.LBB0_1181:
	s_or_b64 exec, exec, s[8:9]
	s_waitcnt lgkmcnt(1)
	ds_read_b128 v[70:73], v100 offset:16384
	s_waitcnt lgkmcnt(1)
	ds_read_b128 v[66:69], v101 offset:16384
	v_add_u32_e32 v100, 32, v64
	v_cmp_lt_i32_e32 vcc, 1, v100
	s_and_saveexec_b64 s[8:9], vcc
	s_cbranch_execz .LBB0_1183
	v_add_u32_e32 v74, -2, v96
	v_add_u32_e32 v78, -4, v96
	v_bitop3_b32 v75, v74, v94, 14 bitop3:0x6c
	v_bitop3_b32 v79, v78, v94, 14 bitop3:0x6c
	v_lshlrev_b32_e32 v75, 3, v75
	v_lshlrev_b32_e32 v79, 3, v79
	v_add3_u32 v75, v97, v75, s7
	v_add3_u32 v79, v97, v79, s7
	ds_read_b128 v[82:85], v75 offset:15872
	ds_read_b128 v[86:89], v79 offset:15360
	v_bitop3_b32 v74, v74, v95, 14 bitop3:0x6c
	v_bitop3_b32 v78, v78, v95, 14 bitop3:0x6c
	v_lshlrev_b32_e32 v74, 3, v74
	v_lshlrev_b32_e32 v78, 3, v78
	v_add3_u32 v74, v97, v74, s7
	v_add3_u32 v78, v97, v78, s7
	ds_read_b128 v[74:77], v74 offset:15872
	ds_read_b128 v[78:81], v78 offset:15360
	s_waitcnt lgkmcnt(2)
	v_lshlrev_b32_e32 v102, 16, v86
	v_and_b32_e32 v103, 0xffff0000, v86
	v_pk_fma_f32 v[102:103], v[20:21], v[102:103], v[60:61]
	v_lshlrev_b32_e32 v104, 16, v82
	v_and_b32_e32 v105, 0xffff0000, v82
	v_lshlrev_b32_e32 v86, 16, v87
	v_and_b32_e32 v87, 0xffff0000, v87
	v_pk_fma_f32 v[102:103], v[24:25], v[104:105], v[102:103]
	v_lshlrev_b32_e32 v104, 16, v70
	v_and_b32_e32 v105, 0xffff0000, v70
	v_pk_fma_f32 v[86:87], v[22:23], v[86:87], v[62:63]
	v_lshlrev_b32_e32 v82, 16, v83
	v_and_b32_e32 v83, 0xffff0000, v83
	v_pk_fma_f32 v[102:103], v[40:41], v[104:105], v[102:103]
	s_waitcnt lgkmcnt(0)
	v_lshlrev_b32_e32 v104, 16, v78
	v_and_b32_e32 v105, 0xffff0000, v78
	v_pk_fma_f32 v[82:83], v[26:27], v[82:83], v[86:87]
	v_lshlrev_b32_e32 v86, 16, v71
	v_and_b32_e32 v87, 0xffff0000, v71
	v_lshlrev_b32_e32 v78, 16, v79
	v_and_b32_e32 v79, 0xffff0000, v79
	v_pk_fma_f32 v[82:83], v[42:43], v[86:87], v[82:83]
	v_pk_fma_f32 v[78:79], v[2:3], v[78:79], v[10:11]
	v_lshlrev_b32_e32 v86, 16, v75
	v_and_b32_e32 v87, 0xffff0000, v75
	v_pk_fma_f32 v[78:79], v[30:31], v[86:87], v[78:79]
	v_lshlrev_b32_e32 v86, 16, v67
	v_and_b32_e32 v87, 0xffff0000, v67
	v_pk_fma_f32 v[78:79], v[46:47], v[86:87], v[78:79]
	v_pk_fma_f32 v[104:105], v[0:1], v[104:105], v[8:9]
	v_mul_f32_e32 v75, 0x3d372713, v78
	v_mul_f32_e32 v75, v78, v75
	v_fma_f32 v75, v78, v75, v78
	v_mul_f32_e32 v75, 0xc0135761, v75
	v_exp_f32_e32 v75, v75
	v_lshlrev_b32_e32 v106, 16, v74
	v_and_b32_e32 v107, 0xffff0000, v74
	v_pk_fma_f32 v[104:105], v[28:29], v[106:107], v[104:105]
	v_add_f32_e32 v75, 1.0, v75
	v_rcp_f32_e32 v86, v75
	v_mul_f32_e32 v75, 0x3d372713, v79
	v_mul_f32_e32 v75, v79, v75
	v_fma_f32 v75, v79, v75, v79
	v_mul_f32_e32 v75, 0xc0135761, v75
	v_exp_f32_e32 v75, v75
	v_lshlrev_b32_e32 v106, 16, v66
	v_and_b32_e32 v107, 0xffff0000, v66
	v_pk_fma_f32 v[104:105], v[44:45], v[106:107], v[104:105]
	v_add_f32_e32 v75, 1.0, v75
	v_rcp_f32_e32 v87, v75
	v_mul_f32_e32 v74, 0x3d372713, v104
	v_mul_f32_e32 v74, v104, v74
	v_fma_f32 v74, v104, v74, v104
	v_pk_mul_f32 v[78:79], v[78:79], v[86:87]
	v_lshlrev_b32_e32 v86, 16, v76
	v_pk_mul_f32 v[78:79], v[82:83], v[78:79]
	v_lshlrev_b32_e32 v82, 16, v84
	v_cvt_pk_bf16_f32 v75, v78, v79
	v_lshlrev_b32_e32 v78, 16, v88
	v_and_b32_e32 v79, 0xffff0000, v88
	v_pk_fma_f32 v[78:79], v[16:17], v[78:79], v[56:57]
	v_and_b32_e32 v83, 0xffff0000, v84
	v_pk_fma_f32 v[78:79], v[32:33], v[82:83], v[78:79]
	v_lshlrev_b32_e32 v82, 16, v72
	v_and_b32_e32 v83, 0xffff0000, v72
	v_pk_fma_f32 v[78:79], v[48:49], v[82:83], v[78:79]
	v_lshlrev_b32_e32 v82, 16, v80
	v_and_b32_e32 v83, 0xffff0000, v80
	v_pk_fma_f32 v[82:83], v[4:5], v[82:83], v[12:13]
	v_and_b32_e32 v87, 0xffff0000, v76
	v_pk_fma_f32 v[82:83], v[36:37], v[86:87], v[82:83]
	v_lshlrev_b32_e32 v86, 16, v68
	v_and_b32_e32 v87, 0xffff0000, v68
	v_pk_fma_f32 v[82:83], v[52:53], v[86:87], v[82:83]
	v_lshlrev_b32_e32 v80, 16, v81
	v_mul_f32_e32 v76, 0x3d372713, v82
	v_mul_f32_e32 v76, v82, v76
	v_fma_f32 v76, v82, v76, v82
	v_mul_f32_e32 v76, 0xc0135761, v76
	v_exp_f32_e32 v76, v76
	v_and_b32_e32 v81, 0xffff0000, v81
	v_pk_fma_f32 v[80:81], v[6:7], v[80:81], v[14:15]
	v_mul_f32_e32 v74, 0x3fcc422a, v74
	v_add_f32_e32 v76, 1.0, v76
	v_rcp_f32_e32 v86, v76
	v_mul_f32_e32 v76, 0x3d372713, v83
	v_mul_f32_e32 v76, v83, v76
	v_fma_f32 v76, v83, v76, v83
	v_mul_f32_e32 v76, 0xc0135761, v76
	v_exp_f32_e32 v76, v76
	v_mul_f32_e32 v74, 0xbfb8aa3b, v74
	v_exp_f32_e32 v74, v74
	v_add_f32_e32 v76, 1.0, v76
	v_rcp_f32_e32 v87, v76
	v_add_f32_e32 v74, 1.0, v74
	v_rcp_f32_e32 v106, v74
	v_mul_f32_e32 v74, 0x3d372713, v105
	v_pk_mul_f32 v[82:83], v[82:83], v[86:87]
	v_mul_f32_e32 v74, v105, v74
	v_pk_mul_f32 v[78:79], v[78:79], v[82:83]
	v_lshlrev_b32_e32 v82, 16, v85
	v_cvt_pk_bf16_f32 v76, v78, v79
	v_lshlrev_b32_e32 v78, 16, v89
	v_and_b32_e32 v79, 0xffff0000, v89
	v_pk_fma_f32 v[78:79], v[18:19], v[78:79], v[58:59]
	v_and_b32_e32 v83, 0xffff0000, v85
	v_pk_fma_f32 v[78:79], v[34:35], v[82:83], v[78:79]
	v_lshlrev_b32_e32 v82, 16, v73
	v_and_b32_e32 v83, 0xffff0000, v73
	v_pk_fma_f32 v[78:79], v[50:51], v[82:83], v[78:79]
	v_lshlrev_b32_e32 v82, 16, v77
	v_and_b32_e32 v83, 0xffff0000, v77
	v_pk_fma_f32 v[80:81], v[38:39], v[82:83], v[80:81]
	v_lshlrev_b32_e32 v82, 16, v69
	v_and_b32_e32 v83, 0xffff0000, v69
	v_pk_fma_f32 v[80:81], v[54:55], v[82:83], v[80:81]
	v_fma_f32 v74, v105, v74, v105
	v_mul_f32_e32 v77, 0x3d372713, v80
	v_mul_f32_e32 v77, v80, v77
	v_fma_f32 v77, v80, v77, v80
	v_mul_f32_e32 v77, 0xc0135761, v77
	v_exp_f32_e32 v77, v77
	v_mul_f32_e32 v74, 0xc0135761, v74
	v_exp_f32_e32 v74, v74
	v_add_f32_e32 v77, 1.0, v77
	v_rcp_f32_e32 v82, v77
	v_mul_f32_e32 v77, 0x3d372713, v81
	v_mul_f32_e32 v77, v81, v77
	v_fma_f32 v77, v81, v77, v81
	v_mul_f32_e32 v77, 0xc0135761, v77
	v_exp_f32_e32 v77, v77
	v_add_f32_e32 v74, 1.0, v74
	v_rcp_f32_e32 v107, v74
	v_add_f32_e32 v77, 1.0, v77
	v_rcp_f32_e32 v83, v77
	v_pk_mul_f32 v[104:105], v[104:105], v[106:107]
	v_pk_mul_f32 v[80:81], v[80:81], v[82:83]
	v_pk_mul_f32 v[102:103], v[102:103], v[104:105]
	v_pk_mul_f32 v[78:79], v[78:79], v[80:81]
	v_cvt_pk_bf16_f32 v74, v102, v103
	v_cvt_pk_bf16_f32 v77, v78, v79
	v_mad_u64_u32 v[78:79], s[22:23], v100, s6, v[90:91]
	global_store_dwordx4 v[78:79], v[74:77], off sc0 sc1
